# row-norm phases (mod-rmsnorm x2, DeltaNet combine norm, final norm): the serialized ds_bpermute butterfly sums replaced by v_permlane32/16_swap + DPP (row_ror/quad_perm/half_mirror) adds, same pairing
# baseline (speedup 1.0000x reference)
.LBB0_217:
	s_or_b64 exec, exec, s[4:5]
	v_mov_b32_e32 v73, v67
	v_mov_b32_e32 v75, v67
	v_lshl_add_u64 v[112:113], v[86:87], 0, v[66:67]
	v_lshl_add_u64 v[116:117], v[86:87], 0, v[72:73]
	v_lshl_add_u64 v[120:121], v[86:87], 0, v[74:75]
	global_load_dwordx4 v[100:103], v[112:113], off nt
	global_load_dwordx4 v[104:107], v[112:113], off offset:1024 nt
	global_load_dwordx4 v[108:111], v[112:113], off offset:2048 nt
	s_nop 0
	global_load_dwordx4 v[112:115], v[112:113], off offset:3072 nt
	s_nop 0
	global_load_dwordx4 v[116:119], v[116:117], off nt
	s_nop 0
	global_load_dwordx4 v[120:123], v[120:121], off nt
	v_mov_b32_e32 v77, v67
	v_mov_b32_e32 v79, v67
	v_lshl_add_u64 v[124:125], v[86:87], 0, v[76:77]
	v_lshl_add_u64 v[86:87], v[86:87], 0, v[78:79]
	global_load_dwordx4 v[124:127], v[124:125], off nt
	s_nop 0
	global_load_dwordx4 v[128:131], v[86:87], off nt
	s_add_i32 s6, s6, 1
	s_add_u32 s2, s2, 0x2000
	v_lshlrev_b64 v[84:85], 12, v[84:85]
	s_addc_u32 s3, s3, 0
	v_lshl_add_u64 v[84:85], v[68:69], 0, v[84:85]
	s_cmpk_eq_u32 s2, 0x8000
	v_lshl_add_u64 v[82:83], v[82:83], 0, 1
	s_waitcnt vmcnt(7)
	v_mul_f32_e32 v71, v101, v101
	s_waitcnt vmcnt(6)
	v_mul_f32_e32 v73, v105, v105
	s_waitcnt vmcnt(5)
	v_mul_f32_e32 v75, v109, v109
	v_fmac_f32_e32 v71, v100, v100
	v_fmac_f32_e32 v73, v104, v104
	s_waitcnt vmcnt(4)
	v_mul_f32_e32 v77, v113, v113
	v_fmac_f32_e32 v75, v108, v108
	s_waitcnt vmcnt(3)
	v_mov_b32_e32 v132, v117
	s_waitcnt vmcnt(2)
	v_mov_b32_e32 v133, v121
	v_fmac_f32_e32 v71, v102, v102
	v_fmac_f32_e32 v73, v106, v106
	v_fmac_f32_e32 v77, v112, v112
	v_mov_b32_e32 v86, v116
	v_mov_b32_e32 v87, v120
	v_fmac_f32_e32 v75, v110, v110
	v_pk_mul_f32 v[132:133], v[132:133], v[132:133]
	v_fmac_f32_e32 v71, v103, v103
	v_fmac_f32_e32 v73, v107, v107
	v_mov_b32_e32 v134, v118
	v_mov_b32_e32 v135, v122
	s_waitcnt vmcnt(1)
	v_mov_b32_e32 v140, v125
	s_waitcnt vmcnt(0)
	v_mov_b32_e32 v141, v129
	v_fmac_f32_e32 v77, v114, v114
	v_fmac_f32_e32 v75, v111, v111
	v_pk_fma_f32 v[86:87], v[86:87], v[86:87], v[132:133]
	v_add_f32_e32 v71, v71, v73
	v_mov_b32_e32 v136, v119
	v_mov_b32_e32 v137, v123
	v_mov_b32_e32 v138, v124
	v_mov_b32_e32 v139, v128
	v_pk_mul_f32 v[140:141], v[140:141], v[140:141]
	v_fmac_f32_e32 v77, v115, v115
	v_pk_fma_f32 v[86:87], v[134:135], v[134:135], v[86:87]
	v_add_f32_e32 v71, v71, v75
	v_mov_b32_e32 v142, v126
	v_mov_b32_e32 v143, v130
	v_pk_fma_f32 v[132:133], v[138:139], v[138:139], v[140:141]
	v_pk_fma_f32 v[86:87], v[136:137], v[136:137], v[86:87]
	v_add_f32_e32 v71, v71, v77
	v_mov_b32_e32 v144, v127
	v_mov_b32_e32 v145, v131
	v_pk_fma_f32 v[132:133], v[142:143], v[142:143], v[132:133]
	v_add_f32_e32 v71, v71, v86
	v_pk_fma_f32 v[132:133], v[144:145], v[144:145], v[132:133]
	v_add_f32_e32 v71, v71, v87
	v_add_f32_e32 v71, v71, v132
	v_add_f32_e32 v71, v71, v133
	s_waitcnt lgkmcnt(0)
	v_mov_b32_e32 v73, v71
	s_nop 1
	v_permlane32_swap_b32_e32 v71, v73
	v_add_f32_e32 v71, v71, v73
	v_mov_b32_e32 v73, v71
	s_nop 1
	v_permlane16_swap_b32_e32 v71, v73
	v_add_f32_e32 v71, v71, v73
	s_nop 1
	v_add_f32_dpp v71, v71, v71 row_ror:8 row_mask:0xf bank_mask:0xf
	s_nop 1
	v_mov_b32_dpp v73, v71 quad_perm:[3,2,1,0] row_mask:0xf bank_mask:0xf
	s_nop 1
	v_add_f32_dpp v71, v73, v71 row_half_mirror row_mask:0xf bank_mask:0xf
	s_nop 1
	v_add_f32_dpp v71, v71, v71 quad_perm:[2,3,0,1] row_mask:0xf bank_mask:0xf
	s_nop 1
	v_add_f32_dpp v71, v71, v71 quad_perm:[1,0,3,2] row_mask:0xf bank_mask:0xf
	v_fmamk_f32 v71, v71, 0x3a000000, v98
	v_mul_f32_e32 v73, 0x4b800000, v71
	v_cmp_gt_f32_e32 vcc, s11, v71
	s_nop 1
	v_cndmask_b32_e32 v71, v71, v73, vcc
	v_rsq_f32_e32 v71, v71
	s_nop 0
	v_mul_f32_e32 v73, 0x45800000, v71
	v_cndmask_b32_e32 v86, v71, v73, vcc
	v_pk_mul_f32 v[102:103], v[102:103], v[86:87] op_sel_hi:[1,0]
	v_pk_mul_f32 v[100:101], v[100:101], v[86:87] op_sel_hi:[1,0]
	v_pk_mul_f32 v[106:107], v[106:107], v[86:87] op_sel_hi:[1,0]
	v_pk_mul_f32 v[104:105], v[104:105], v[86:87] op_sel_hi:[1,0]
	v_pk_mul_f32 v[110:111], v[110:111], v[86:87] op_sel_hi:[1,0]
	v_pk_mul_f32 v[108:109], v[108:109], v[86:87] op_sel_hi:[1,0]
	v_pk_mul_f32 v[114:115], v[114:115], v[86:87] op_sel_hi:[1,0]
	v_pk_mul_f32 v[112:113], v[112:113], v[86:87] op_sel_hi:[1,0]
	v_pk_mul_f32 v[118:119], v[118:119], v[86:87] op_sel_hi:[1,0]
	v_pk_mul_f32 v[116:117], v[116:117], v[86:87] op_sel_hi:[1,0]
	v_pk_mul_f32 v[122:123], v[122:123], v[86:87] op_sel_hi:[1,0]
	v_pk_mul_f32 v[120:121], v[120:121], v[86:87] op_sel_hi:[1,0]
	v_pk_mul_f32 v[126:127], v[126:127], v[86:87] op_sel_hi:[1,0]
	v_pk_mul_f32 v[124:125], v[124:125], v[86:87] op_sel_hi:[1,0]
	v_pk_mul_f32 v[130:131], v[130:131], v[86:87] op_sel_hi:[1,0]
	v_pk_mul_f32 v[86:87], v[128:129], v[86:87] op_sel_hi:[1,0]
	v_pk_fma_f32 v[100:101], v[0:1], v[100:101], v[8:9]
	v_pk_fma_f32 v[102:103], v[2:3], v[102:103], v[10:11]
	v_pk_fma_f32 v[104:105], v[4:5], v[104:105], v[12:13]
	v_pk_fma_f32 v[106:107], v[6:7], v[106:107], v[14:15]
	v_pk_fma_f32 v[108:109], v[108:109], v[16:17], v[24:25]
	v_pk_fma_f32 v[110:111], v[110:111], v[18:19], v[26:27]
	v_pk_fma_f32 v[112:113], v[112:113], v[20:21], v[28:29]
	v_pk_fma_f32 v[114:115], v[114:115], v[22:23], v[30:31]
	v_pk_fma_f32 v[116:117], v[116:117], v[32:33], v[40:41]
	v_pk_fma_f32 v[118:119], v[118:119], v[34:35], v[42:43]
	v_pk_fma_f32 v[120:121], v[120:121], v[36:37], v[44:45]
	v_pk_fma_f32 v[122:123], v[122:123], v[38:39], v[46:47]
	v_pk_fma_f32 v[124:125], v[124:125], v[48:49], v[56:57]
	v_pk_fma_f32 v[126:127], v[126:127], v[50:51], v[58:59]
	v_pk_fma_f32 v[86:87], v[86:87], v[52:53], v[60:61]
	v_pk_fma_f32 v[128:129], v[130:131], v[54:55], v[62:63]
	v_cvt_pk_bf16_f32 v103, v102, v103
	v_cvt_pk_bf16_f32 v102, v100, v101
	v_cvt_pk_bf16_f32 v101, v106, v107
	v_cvt_pk_bf16_f32 v100, v104, v105
	v_cvt_pk_bf16_f32 v105, v110, v111
	v_cvt_pk_bf16_f32 v104, v108, v109
	v_cvt_pk_bf16_f32 v107, v114, v115
	v_cvt_pk_bf16_f32 v106, v112, v113
	v_cvt_pk_bf16_f32 v109, v118, v119
	v_cvt_pk_bf16_f32 v108, v116, v117
	v_cvt_pk_bf16_f32 v111, v122, v123
	v_cvt_pk_bf16_f32 v110, v120, v121
	v_cvt_pk_bf16_f32 v113, v126, v127
	v_cvt_pk_bf16_f32 v112, v124, v125
	v_cvt_pk_bf16_f32 v115, v128, v129
	v_cvt_pk_bf16_f32 v114, v86, v87
	global_store_dwordx2 v[84:85], v[102:103], off
	global_store_dwordx2 v[84:85], v[100:101], off offset:512
	global_store_dwordx2 v[84:85], v[104:105], off offset:1024
	global_store_dwordx2 v[84:85], v[106:107], off offset:1536
	global_store_dwordx2 v[84:85], v[108:109], off offset:2048
	global_store_dwordx2 v[84:85], v[110:111], off offset:2560
	global_store_dwordx2 v[84:85], v[112:113], off offset:3072
	global_store_dwordx2 v[84:85], v[114:115], off offset:3584
	s_cbranch_scc1 .LBB0_213

.LBB0_855:
	v_ashrrev_i32_e32 v28, 3, v17
	v_ashrrev_i32_e32 v29, 31, v28
	v_mad_i64_i32 v[30:31], s[12:13], v28, s7, v[8:9]
	v_lshlrev_b64 v[20:21], 12, v[28:29]
	v_lshl_add_u64 v[22:23], v[30:31], 0, v[4:5]
	v_or_b32_e32 v21, v21, v7
	v_or_b32_e32 v20, v20, v6
	v_lshl_add_u64 v[32:33], v[22:23], 0, v[10:11]
	v_lshl_add_u64 v[34:35], s[0:1], 0, v[20:21]
	v_lshl_add_u64 v[36:37], s[4:5], 0, v[20:21]
	v_add_co_u32_e32 v32, vcc, s8, v32
	global_load_dwordx4 v[20:23], v[34:35], off
	global_load_dwordx4 v[24:27], v[36:37], off
	v_addc_co_u32_e32 v33, vcc, 0, v33, vcc
	global_load_dwordx2 v[32:33], v[32:33], off
	v_mad_i64_i32 v[28:29], s[12:13], v28, s10, v[30:31]
	v_lshl_add_u64 v[28:29], v[28:29], 0, v[4:5]
	v_lshl_add_u64 v[28:29], v[28:29], 0, v[10:11]
	v_add_co_u32_e32 v28, vcc, 0x6700000, v28
	s_add_i32 s11, s11, s84
	s_nop 0
	v_addc_co_u32_e32 v29, vcc, 0, v29, vcc
	v_add_u32_e32 v17, s6, v17
	s_cmpk_lt_i32 s11, 0x1000
	s_waitcnt vmcnt(1)
	v_pk_add_f32 v[20:21], v[20:21], v[24:25]
	v_pk_add_f32 v[22:23], v[22:23], v[26:27]
	v_pk_mul_f32 v[24:25], v[20:21], v[20:21]
	v_pk_mul_f32 v[30:31], v[22:23], v[22:23]
	s_waitcnt vmcnt(0)
	v_and_b32_e32 v35, 0xffff0000, v33
	v_add_f32_e32 v24, v24, v25
	v_lshlrev_b32_e32 v26, 16, v32
	v_lshlrev_b32_e32 v34, 16, v33
	v_mul_f32_e32 v33, 0xbfb8aa3b, v35
	v_add_f32_e32 v24, v24, v30
	v_and_b32_e32 v27, 0xffff0000, v32
	v_mul_f32_e32 v19, 0xbfb8aa3b, v26
	v_exp_f32_e32 v30, v33
	v_add_f32_e32 v33, v24, v31
	v_mul_f32_e32 v32, 0xbfb8aa3b, v27
	v_mul_f32_e32 v25, 0xbfb8aa3b, v34
	v_exp_f32_e32 v19, v19
	v_exp_f32_e32 v32, v32
	v_exp_f32_e32 v25, v25
	v_add_f32_e32 v19, 1.0, v19
	v_rcp_f32_e32 v24, v19
	v_add_f32_e32 v31, 1.0, v32
	v_add_f32_e32 v32, 1.0, v25
	v_add_f32_dpp v19, v33, v33 quad_perm:[1,0,3,2] row_mask:0xf bank_mask:0xf
	v_add_f32_e32 v37, 1.0, v30
	v_rcp_f32_e32 v30, v32
	v_rcp_f32_e32 v25, v31
	v_rcp_f32_e32 v31, v37
	v_add_f32_dpp v19, v19, v19 quad_perm:[2,3,0,1] row_mask:0xf bank_mask:0xf
	v_pk_mul_f32 v[24:25], v[24:25], v[26:27]
	v_pk_mul_f32 v[26:27], v[30:31], v[34:35]
	v_add_f32_dpp v19, v19, v19 row_half_mirror row_mask:0xf bank_mask:0xf
	s_nop 1
	v_add_f32_dpp v19, v19, v19 row_mirror row_mask:0xf bank_mask:0xf
	v_mov_b32_e32 v30, v19
	s_nop 1
	v_permlane16_swap_b32_e32 v19, v30
	v_add_f32_e32 v19, v19, v30
	v_fmamk_f32 v19, v19, 0x3c000000, v18
	v_mul_f32_e32 v30, 0x4b800000, v19
	v_cmp_gt_f32_e32 vcc, s9, v19
	s_nop 1
	v_cndmask_b32_e32 v19, v19, v30, vcc
	v_rsq_f32_e32 v19, v19
	s_nop 0
	v_mul_f32_e32 v30, 0x45800000, v19
	v_cndmask_b32_e32 v30, v19, v30, vcc
	v_pk_mul_f32 v[20:21], v[20:21], v[30:31] op_sel_hi:[1,0]
	v_pk_mul_f32 v[22:23], v[22:23], v[30:31] op_sel_hi:[1,0]
	v_pk_mul_f32 v[20:21], v[0:1], v[20:21]
	v_pk_mul_f32 v[22:23], v[2:3], v[22:23]
	v_pk_mul_f32 v[20:21], v[24:25], v[20:21]
	v_pk_mul_f32 v[22:23], v[26:27], v[22:23]
	s_nop 0
	v_cvt_pk_bf16_f32 v23, v22, v23
	v_cvt_pk_bf16_f32 v22, v20, v21
	global_store_dwordx2 v[28:29], v[22:23], off offset:2048
	s_cbranch_scc1 .LBB0_855

.LBB0_985:
	v_lshl_add_u64 v[74:75], v[72:73], 0, s[8:9]
	v_add_co_u32_e32 v86, vcc, 0xea00000, v74
	v_add_co_u32_e64 v88, s[0:1], s13, v74
	s_nop 0
	v_addc_co_u32_e32 v87, vcc, 0, v75, vcc
	v_addc_co_u32_e64 v89, s[0:1], 0, v75, s[0:1]
	global_load_dwordx2 v[74:75], v[86:87], off
	global_load_dwordx2 v[90:91], v[86:87], off offset:512
	global_load_dwordx2 v[92:93], v[86:87], off offset:1024
	global_load_dwordx2 v[94:95], v[86:87], off offset:1536
	global_load_dwordx2 v[96:97], v[86:87], off offset:2048
	global_load_dwordx2 v[98:99], v[86:87], off offset:2560
	global_load_dwordx2 v[100:101], v[86:87], off offset:3072
	global_load_dwordx2 v[102:103], v[86:87], off offset:3584
	s_add_u32 s8, s8, 0x1000
	s_addc_u32 s9, s9, 0
	s_cmpk_eq_i32 s8, 0x4000
	s_waitcnt vmcnt(7)
	v_and_b32_e32 v87, 0xffff0000, v74
	v_lshlrev_b32_e32 v86, 16, v74
	v_and_b32_e32 v105, 0xffff0000, v75
	v_lshlrev_b32_e32 v104, 16, v75
	s_waitcnt vmcnt(6)
	v_and_b32_e32 v75, 0xffff0000, v90
	v_lshlrev_b32_e32 v74, 16, v90
	v_and_b32_e32 v107, 0xffff0000, v91
	v_lshlrev_b32_e32 v106, 16, v91
	s_waitcnt vmcnt(5)
	v_and_b32_e32 v91, 0xffff0000, v92
	v_lshlrev_b32_e32 v90, 16, v92
	v_and_b32_e32 v109, 0xffff0000, v93
	v_lshlrev_b32_e32 v108, 16, v93
	s_waitcnt vmcnt(4)
	v_and_b32_e32 v93, 0xffff0000, v94
	v_lshlrev_b32_e32 v92, 16, v94
	v_and_b32_e32 v111, 0xffff0000, v95
	v_lshlrev_b32_e32 v110, 16, v95
	s_waitcnt vmcnt(3)
	v_and_b32_e32 v95, 0xffff0000, v96
	v_lshlrev_b32_e32 v94, 16, v96
	v_and_b32_e32 v113, 0xffff0000, v97
	v_lshlrev_b32_e32 v112, 16, v97
	s_waitcnt vmcnt(2)
	v_and_b32_e32 v97, 0xffff0000, v98
	v_lshlrev_b32_e32 v96, 16, v98
	v_and_b32_e32 v115, 0xffff0000, v99
	v_lshlrev_b32_e32 v114, 16, v99
	s_waitcnt vmcnt(1)
	v_and_b32_e32 v99, 0xffff0000, v100
	v_lshlrev_b32_e32 v98, 16, v100
	v_and_b32_e32 v117, 0xffff0000, v101
	v_lshlrev_b32_e32 v116, 16, v101
	s_waitcnt vmcnt(0)
	v_and_b32_e32 v101, 0xffff0000, v102
	v_lshlrev_b32_e32 v100, 16, v102
	v_and_b32_e32 v119, 0xffff0000, v103
	v_lshlrev_b32_e32 v118, 16, v103
	v_pk_mul_f32 v[102:103], v[86:87], v[86:87]
	v_pk_mul_f32 v[122:123], v[74:75], v[74:75]
	v_pk_mul_f32 v[120:121], v[104:105], v[104:105]
	v_pk_mul_f32 v[124:125], v[106:107], v[106:107]
	v_pk_mul_f32 v[126:127], v[90:91], v[90:91]
	v_add_f32_e32 v71, v122, v123
	v_add_f32_e32 v85, v102, v103
	v_pk_mul_f32 v[128:129], v[108:109], v[108:109]
	v_pk_mul_f32 v[130:131], v[92:93], v[92:93]
	v_mov_b32_e32 v136, v95
	v_mov_b32_e32 v137, v97
	v_add_f32_e32 v126, v126, v127
	v_add_f32_e32 v71, v124, v71
	v_add_f32_e32 v85, v120, v85
	v_pk_mul_f32 v[132:133], v[110:111], v[110:111]
	v_mov_b32_e32 v134, v94
	v_mov_b32_e32 v135, v96
	v_pk_mul_f32 v[136:137], v[136:137], v[136:137]
	v_add_f32_e32 v127, v130, v131
	v_add_f32_e32 v120, v128, v126
	v_add_f32_e32 v71, v125, v71
	v_add_f32_e32 v85, v121, v85
	v_mov_b32_e32 v138, v112
	v_mov_b32_e32 v139, v114
	v_mov_b32_e32 v144, v99
	v_mov_b32_e32 v145, v101
	v_pk_fma_f32 v[102:103], v[134:135], v[134:135], v[136:137]
	v_add_f32_e32 v124, v132, v127
	v_add_f32_e32 v125, v129, v120
	v_add_f32_e32 v71, v85, v71
	v_mov_b32_e32 v140, v113
	v_mov_b32_e32 v141, v115
	v_mov_b32_e32 v142, v98
	v_mov_b32_e32 v143, v100
	v_pk_mul_f32 v[144:145], v[144:145], v[144:145]
	v_pk_fma_f32 v[102:103], v[138:139], v[138:139], v[102:103]
	v_add_f32_e32 v124, v133, v124
	v_add_f32_e32 v71, v71, v125
	v_mov_b32_e32 v146, v116
	v_mov_b32_e32 v147, v118
	v_pk_fma_f32 v[122:123], v[142:143], v[142:143], v[144:145]
	v_pk_fma_f32 v[102:103], v[140:141], v[140:141], v[102:103]
	v_add_f32_e32 v71, v71, v124
	v_mov_b32_e32 v148, v117
	v_mov_b32_e32 v149, v119
	v_pk_fma_f32 v[122:123], v[146:147], v[146:147], v[122:123]
	v_add_f32_e32 v71, v71, v102
	v_pk_fma_f32 v[120:121], v[148:149], v[148:149], v[122:123]
	v_add_f32_e32 v71, v71, v103
	v_add_f32_e32 v71, v71, v120
	v_add_f32_e32 v71, v71, v121
	s_waitcnt lgkmcnt(0)
	v_mov_b32_e32 v85, v71
	s_nop 1
	v_permlane32_swap_b32_e32 v71, v85
	v_add_f32_e32 v71, v71, v85
	v_mov_b32_e32 v85, v71
	s_nop 1
	v_permlane16_swap_b32_e32 v71, v85
	v_add_f32_e32 v71, v71, v85
	s_nop 1
	v_add_f32_dpp v71, v71, v71 row_ror:8 row_mask:0xf bank_mask:0xf
	s_nop 1
	v_mov_b32_dpp v85, v71 quad_perm:[3,2,1,0] row_mask:0xf bank_mask:0xf
	s_nop 1
	v_add_f32_dpp v71, v85, v71 row_half_mirror row_mask:0xf bank_mask:0xf
	s_nop 1
	v_add_f32_dpp v71, v71, v71 quad_perm:[2,3,0,1] row_mask:0xf bank_mask:0xf
	s_nop 1
	v_add_f32_dpp v71, v71, v71 quad_perm:[1,0,3,2] row_mask:0xf bank_mask:0xf
	v_fmamk_f32 v71, v71, 0x3a000000, v84
	v_mul_f32_e32 v85, 0x4b800000, v71
	v_cmp_gt_f32_e32 vcc, s12, v71
	s_nop 1
	v_cndmask_b32_e32 v71, v71, v85, vcc
	v_rsq_f32_e32 v71, v71
	s_nop 0
	v_mul_f32_e32 v85, 0x45800000, v71
	v_cndmask_b32_e32 v102, v71, v85, vcc
	v_pk_mul_f32 v[104:105], v[102:103], v[104:105] op_sel_hi:[0,1]
	v_pk_mul_f32 v[86:87], v[102:103], v[86:87] op_sel_hi:[0,1]
	v_pk_mul_f32 v[106:107], v[102:103], v[106:107] op_sel_hi:[0,1]
	v_pk_mul_f32 v[74:75], v[102:103], v[74:75] op_sel_hi:[0,1]
	v_pk_mul_f32 v[108:109], v[102:103], v[108:109] op_sel_hi:[0,1]
	v_pk_mul_f32 v[90:91], v[102:103], v[90:91] op_sel_hi:[0,1]
	v_pk_mul_f32 v[110:111], v[102:103], v[110:111] op_sel_hi:[0,1]
	v_pk_mul_f32 v[92:93], v[102:103], v[92:93] op_sel_hi:[0,1]
	v_pk_mul_f32 v[112:113], v[102:103], v[112:113] op_sel_hi:[0,1]
	v_pk_mul_f32 v[94:95], v[102:103], v[94:95] op_sel_hi:[0,1]
	v_pk_mul_f32 v[114:115], v[102:103], v[114:115] op_sel_hi:[0,1]
	v_pk_mul_f32 v[96:97], v[102:103], v[96:97] op_sel_hi:[0,1]
	v_pk_mul_f32 v[116:117], v[102:103], v[116:117] op_sel_hi:[0,1]
	v_pk_mul_f32 v[98:99], v[102:103], v[98:99] op_sel_hi:[0,1]
	v_pk_mul_f32 v[118:119], v[102:103], v[118:119] op_sel_hi:[0,1]
	v_pk_mul_f32 v[100:101], v[102:103], v[100:101] op_sel_hi:[0,1]
	v_pk_fma_f32 v[86:87], v[0:1], v[86:87], v[8:9]
	v_pk_fma_f32 v[102:103], v[2:3], v[104:105], v[10:11]
	v_pk_fma_f32 v[74:75], v[4:5], v[74:75], v[12:13]
	v_pk_fma_f32 v[104:105], v[6:7], v[106:107], v[14:15]
	v_pk_fma_f32 v[90:91], v[90:91], v[16:17], v[24:25]
	v_pk_fma_f32 v[106:107], v[108:109], v[18:19], v[26:27]
	v_pk_fma_f32 v[92:93], v[92:93], v[20:21], v[28:29]
	v_pk_fma_f32 v[108:109], v[110:111], v[22:23], v[30:31]
	v_pk_fma_f32 v[94:95], v[94:95], v[32:33], v[40:41]
	v_pk_fma_f32 v[110:111], v[112:113], v[34:35], v[42:43]
	v_pk_fma_f32 v[96:97], v[96:97], v[36:37], v[44:45]
	v_pk_fma_f32 v[112:113], v[114:115], v[38:39], v[46:47]
	v_pk_fma_f32 v[98:99], v[98:99], v[48:49], v[56:57]
	v_pk_fma_f32 v[114:115], v[116:117], v[50:51], v[58:59]
	v_pk_fma_f32 v[100:101], v[100:101], v[52:53], v[60:61]
	v_pk_fma_f32 v[116:117], v[118:119], v[54:55], v[62:63]
	v_cvt_pk_bf16_f32 v103, v102, v103
	v_cvt_pk_bf16_f32 v102, v86, v87
	v_cvt_pk_bf16_f32 v87, v104, v105
	v_cvt_pk_bf16_f32 v86, v74, v75
	v_cvt_pk_bf16_f32 v75, v106, v107
	v_cvt_pk_bf16_f32 v74, v90, v91
	v_cvt_pk_bf16_f32 v91, v108, v109
	v_cvt_pk_bf16_f32 v90, v92, v93
	v_cvt_pk_bf16_f32 v93, v110, v111
	v_cvt_pk_bf16_f32 v92, v94, v95
	v_cvt_pk_bf16_f32 v95, v112, v113
	v_cvt_pk_bf16_f32 v94, v96, v97
	v_cvt_pk_bf16_f32 v97, v114, v115
	v_cvt_pk_bf16_f32 v96, v98, v99
	v_cvt_pk_bf16_f32 v99, v116, v117
	v_cvt_pk_bf16_f32 v98, v100, v101
	global_store_dwordx2 v[88:89], v[102:103], off
	global_store_dwordx2 v[88:89], v[86:87], off offset:512
	global_store_dwordx2 v[88:89], v[74:75], off offset:1024
	global_store_dwordx2 v[88:89], v[90:91], off offset:1536
	global_store_dwordx2 v[88:89], v[92:93], off offset:2048
	global_store_dwordx2 v[88:89], v[94:95], off offset:2560
	global_store_dwordx2 v[88:89], v[96:97], off offset:3072
	global_store_dwordx2 v[88:89], v[98:99], off offset:3584
	s_cbranch_scc0 .LBB0_985
	s_add_i32 s14, s14, s84
	s_cmpk_gt_i32 s14, 0xff
	v_add_u32_e32 v70, s10, v70
	s_cbranch_scc0 .LBB0_982

.LBB0_1531:
	v_ashrrev_i32_e32 v1, 31, v0
	v_lshlrev_b64 v[32:33], 12, v[0:1]
	v_lshl_add_u64 v[36:37], v[14:15], 0, v[32:33]
	global_load_dwordx2 v[38:39], v[36:37], off nt
	global_load_dwordx2 v[40:41], v[36:37], off offset:512 nt
	global_load_dwordx2 v[42:43], v[36:37], off offset:1024 nt
	global_load_dwordx2 v[44:45], v[36:37], off offset:1536 nt
	global_load_dwordx2 v[46:47], v[36:37], off offset:2048 nt
	global_load_dwordx2 v[48:49], v[36:37], off offset:2560 nt
	global_load_dwordx2 v[50:51], v[36:37], off offset:3072 nt
	global_load_dwordx2 v[52:53], v[36:37], off offset:3584 nt
	s_waitcnt vmcnt(7)
	v_and_b32_e32 v37, 0xffff0000, v38
	v_lshlrev_b32_e32 v36, 16, v38
	v_and_b32_e32 v55, 0xffff0000, v39
	v_lshlrev_b32_e32 v54, 16, v39
	s_waitcnt vmcnt(6)
	v_and_b32_e32 v39, 0xffff0000, v40
	v_lshlrev_b32_e32 v38, 16, v40
	v_and_b32_e32 v57, 0xffff0000, v41
	v_lshlrev_b32_e32 v56, 16, v41
	s_waitcnt vmcnt(5)
	v_and_b32_e32 v41, 0xffff0000, v42
	v_lshlrev_b32_e32 v40, 16, v42
	v_and_b32_e32 v59, 0xffff0000, v43
	v_lshlrev_b32_e32 v58, 16, v43
	s_waitcnt vmcnt(4)
	v_and_b32_e32 v43, 0xffff0000, v44
	v_lshlrev_b32_e32 v42, 16, v44
	v_and_b32_e32 v61, 0xffff0000, v45
	v_lshlrev_b32_e32 v60, 16, v45
	s_waitcnt vmcnt(3)
	v_and_b32_e32 v45, 0xffff0000, v46
	v_lshlrev_b32_e32 v44, 16, v46
	v_and_b32_e32 v63, 0xffff0000, v47
	v_lshlrev_b32_e32 v62, 16, v47
	s_waitcnt vmcnt(2)
	v_and_b32_e32 v47, 0xffff0000, v48
	v_lshlrev_b32_e32 v46, 16, v48
	v_and_b32_e32 v65, 0xffff0000, v49
	v_lshlrev_b32_e32 v64, 16, v49
	s_waitcnt vmcnt(1)
	v_and_b32_e32 v49, 0xffff0000, v50
	v_lshlrev_b32_e32 v48, 16, v50
	v_and_b32_e32 v67, 0xffff0000, v51
	v_lshlrev_b32_e32 v66, 16, v51
	s_waitcnt vmcnt(0)
	v_and_b32_e32 v51, 0xffff0000, v52
	v_lshlrev_b32_e32 v50, 16, v52
	v_and_b32_e32 v69, 0xffff0000, v53
	v_lshlrev_b32_e32 v68, 16, v53
	v_pk_mul_f32 v[52:53], v[36:37], v[36:37]
	v_pk_mul_f32 v[72:73], v[38:39], v[38:39]
	v_pk_mul_f32 v[70:71], v[54:55], v[54:55]
	v_pk_mul_f32 v[74:75], v[56:57], v[56:57]
	v_pk_mul_f32 v[76:77], v[40:41], v[40:41]
	v_add_f32_e32 v31, v72, v73
	v_add_f32_e32 v100, v52, v53
	v_pk_mul_f32 v[78:79], v[58:59], v[58:59]
	v_pk_mul_f32 v[80:81], v[42:43], v[42:43]
	v_mov_b32_e32 v86, v45
	v_mov_b32_e32 v87, v47
	v_add_f32_e32 v76, v76, v77
	v_add_f32_e32 v31, v74, v31
	v_add_f32_e32 v70, v70, v100
	v_pk_mul_f32 v[82:83], v[60:61], v[60:61]
	v_mov_b32_e32 v84, v44
	v_mov_b32_e32 v85, v46
	v_pk_mul_f32 v[86:87], v[86:87], v[86:87]
	v_add_f32_e32 v77, v80, v81
	v_add_f32_e32 v74, v78, v76
	v_add_f32_e32 v31, v75, v31
	v_add_f32_e32 v75, v71, v70
	v_mov_b32_e32 v88, v62
	v_mov_b32_e32 v89, v64
	v_mov_b32_e32 v94, v49
	v_mov_b32_e32 v95, v51
	v_pk_fma_f32 v[52:53], v[84:85], v[84:85], v[86:87]
	v_add_f32_e32 v76, v82, v77
	v_add_f32_e32 v74, v79, v74
	v_add_f32_e32 v31, v75, v31
	v_mov_b32_e32 v90, v63
	v_mov_b32_e32 v91, v65
	v_mov_b32_e32 v92, v48
	v_mov_b32_e32 v93, v50
	v_pk_mul_f32 v[94:95], v[94:95], v[94:95]
	v_pk_fma_f32 v[52:53], v[88:89], v[88:89], v[52:53]
	v_add_f32_e32 v76, v83, v76
	v_add_f32_e32 v31, v31, v74
	v_mov_b32_e32 v96, v66
	v_mov_b32_e32 v97, v68
	v_pk_fma_f32 v[72:73], v[92:93], v[92:93], v[94:95]
	v_pk_fma_f32 v[52:53], v[90:91], v[90:91], v[52:53]
	v_add_f32_e32 v31, v31, v76
	v_mov_b32_e32 v98, v67
	v_mov_b32_e32 v99, v69
	v_pk_fma_f32 v[72:73], v[96:97], v[96:97], v[72:73]
	v_add_f32_e32 v31, v31, v52
	v_pk_fma_f32 v[70:71], v[98:99], v[98:99], v[72:73]
	v_add_f32_e32 v31, v31, v53
	v_add_f32_e32 v31, v31, v70
	v_add_f32_e32 v31, v31, v71
	s_waitcnt lgkmcnt(0)
	v_mov_b32_e32 v52, v31
	s_nop 1
	v_permlane32_swap_b32_e32 v31, v52
	v_add_f32_e32 v31, v31, v52
	v_mov_b32_e32 v52, v31
	s_nop 1
	v_permlane16_swap_b32_e32 v31, v52
	v_add_f32_e32 v31, v31, v52
	s_nop 1
	v_add_f32_dpp v31, v31, v31 row_ror:8 row_mask:0xf bank_mask:0xf
	s_nop 1
	v_mov_b32_dpp v52, v31 quad_perm:[3,2,1,0] row_mask:0xf bank_mask:0xf
	s_nop 1
	v_add_f32_dpp v31, v52, v31 row_half_mirror row_mask:0xf bank_mask:0xf
	s_nop 1
	v_add_f32_dpp v31, v31, v31 quad_perm:[2,3,0,1] row_mask:0xf bank_mask:0xf
	s_nop 1
	v_add_f32_dpp v31, v31, v31 quad_perm:[1,0,3,2] row_mask:0xf bank_mask:0xf
	v_fmamk_f32 v31, v31, 0x3a000000, v30
	v_mul_f32_e32 v52, 0x4b800000, v31
	v_cmp_gt_f32_e32 vcc, s3, v31
	s_nop 1
	v_cndmask_b32_e32 v31, v31, v52, vcc
	v_rsq_f32_e32 v31, v31
	v_lshlrev_b64 v[52:53], 13, v[0:1]
	v_lshl_add_u64 v[52:53], s[78:79], 0, v[52:53]
	v_lshl_add_u64 v[70:71], v[52:53], 0, v[2:3]
	v_mul_f32_e32 v1, 0x45800000, v31
	v_cndmask_b32_e32 v72, v31, v1, vcc
	v_pk_mul_f32 v[36:37], v[72:73], v[36:37] op_sel_hi:[0,1]
	v_pk_mul_f32 v[54:55], v[72:73], v[54:55] op_sel_hi:[0,1]
	v_pk_mul_f32 v[34:35], v[106:107], v[54:55]
	v_pk_mul_f32 v[32:33], v[104:105], v[36:37]
	global_store_dwordx4 v[70:71], v[32:35], off nt
	v_pk_mul_f32 v[36:37], v[72:73], v[56:57] op_sel_hi:[0,1]
	v_pk_mul_f32 v[38:39], v[72:73], v[38:39] op_sel_hi:[0,1]
	v_add_u32_e32 v0, s2, v0
	v_cmp_lt_i32_e32 vcc, s4, v0
	s_or_b64 s[0:1], vcc, s[0:1]
	v_pk_mul_f32 v[32:33], v[108:109], v[38:39]
	v_pk_mul_f32 v[34:35], v[110:111], v[36:37]
	global_store_dwordx4 v[70:71], v[32:35], off offset:1024 nt
	v_pk_mul_f32 v[36:37], v[72:73], v[58:59] op_sel_hi:[0,1]
	v_pk_mul_f32 v[38:39], v[72:73], v[40:41] op_sel_hi:[0,1]
	v_pk_mul_f32 v[40:41], v[72:73], v[44:45] op_sel_hi:[0,1]
	v_pk_mul_f32 v[32:33], v[112:113], v[38:39]
	v_pk_mul_f32 v[34:35], v[114:115], v[36:37]
	global_store_dwordx4 v[70:71], v[32:35], off offset:2048 nt
	v_pk_mul_f32 v[36:37], v[72:73], v[60:61] op_sel_hi:[0,1]
	v_pk_mul_f32 v[38:39], v[72:73], v[42:43] op_sel_hi:[0,1]
	v_pk_mul_f32 v[32:33], v[116:117], v[38:39]
	v_pk_mul_f32 v[34:35], v[118:119], v[36:37]
	global_store_dwordx4 v[70:71], v[32:35], off offset:3072 nt
	v_pk_mul_f32 v[38:39], v[72:73], v[62:63] op_sel_hi:[0,1]
	v_lshl_add_u64 v[36:37], v[52:53], 0, v[16:17]
	v_pk_mul_f32 v[32:33], v[40:41], v[120:121]
	v_pk_mul_f32 v[34:35], v[38:39], v[122:123]
	global_store_dwordx4 v[36:37], v[32:35], off nt
	v_pk_mul_f32 v[38:39], v[72:73], v[64:65] op_sel_hi:[0,1]
	v_pk_mul_f32 v[40:41], v[72:73], v[46:47] op_sel_hi:[0,1]
	v_lshl_add_u64 v[36:37], v[52:53], 0, v[18:19]
	v_pk_mul_f32 v[32:33], v[40:41], v[124:125]
	v_pk_mul_f32 v[34:35], v[38:39], v[126:127]
	global_store_dwordx4 v[36:37], v[32:35], off nt
	v_pk_mul_f32 v[38:39], v[72:73], v[66:67] op_sel_hi:[0,1]
	v_pk_mul_f32 v[40:41], v[72:73], v[48:49] op_sel_hi:[0,1]
	v_lshl_add_u64 v[36:37], v[52:53], 0, v[20:21]
	v_pk_mul_f32 v[32:33], v[40:41], v[128:129]
	v_pk_mul_f32 v[34:35], v[38:39], v[130:131]
	global_store_dwordx4 v[36:37], v[32:35], off nt
	v_pk_mul_f32 v[38:39], v[72:73], v[68:69] op_sel_hi:[0,1]
	v_pk_mul_f32 v[40:41], v[72:73], v[50:51] op_sel_hi:[0,1]
	v_lshl_add_u64 v[36:37], v[52:53], 0, v[22:23]
	v_pk_mul_f32 v[32:33], v[40:41], v[132:133]
	v_pk_mul_f32 v[34:35], v[38:39], v[134:135]
	global_store_dwordx4 v[36:37], v[32:35], off nt
	s_andn2_b64 exec, exec, s[0:1]
	s_cbranch_execnz .LBB0_1531
